# k/v cache shift copy moved out of phase 0 and overlapped with the layer-0 gate/up GEMM K-loops (one float4 per thread per iteration, load in iteration k, store in k+1, exec-masked, skipped once a wave
# speedup vs baseline: 1.0132x; 1.0132x over previous
.LBB0_680:
	v_lshl_add_u64 v[10:11], s[8:9], 0, v[0:1]
	v_mov_b32_e32 v131, v1
	v_lshl_add_u64 v[12:13], s[8:9], 0, v[130:131]
	s_add_i32 m0, s24, 0x18000
	v_lshl_add_u64 v[10:11], v[10:11], 0, s[0:1]
	v_lshl_add_u64 v[14:15], s[10:11], 0, v[0:1]
	s_waitcnt vmcnt(2)
	s_barrier
	global_load_lds_dwordx4 v[10:11], off
	v_lshl_add_u64 v[10:11], v[12:13], 0, s[0:1]
	s_add_i32 m0, s24, 0x1a000
	s_add_i32 s28, s24, 0x8000
	s_add_i32 s29, s24, 0xa000
	v_lshl_add_u64 v[16:17], s[10:11], 0, v[130:131]
	global_load_lds_dwordx4 v[10:11], off
	v_lshl_add_u64 v[10:11], v[14:15], 0, s[0:1]
	s_mov_b32 m0, s28
	s_add_u32 s8, s8, 0x40080
	global_load_lds_dwordx4 v[10:11], off
	v_lshl_add_u64 v[10:11], v[16:17], 0, s[0:1]
	s_mov_b32 m0, s29
	s_addc_u32 s9, s9, 0
	global_load_lds_dwordx4 v[10:11], off
	s_add_i32 m0, s24, 0x1c000
	v_lshl_add_u64 v[10:11], s[8:9], 0, v[0:1]
	global_load_lds_dwordx4 v[10:11], off
	v_lshl_add_u64 v[10:11], s[8:9], 0, v[130:131]
	s_add_i32 m0, s24, 0x1e000
	s_nop 0
	global_load_lds_dwordx4 v[10:11], off
	s_waitcnt vmcnt(6)
	s_barrier
	s_and_saveexec_b64 s[8:9], s[40:41]
	v_lshl_add_u32 v9, v146, 2, 0
	v_add_u32_e32 v9, 0x21040, v9
	v_add_f32_e32 v176, v168, v169
	v_add_f32_e32 v177, v170, v171
	v_add_f32_e32 v176, v176, v177
	v_add_f32_e32 v177, v164, v165
	v_add_f32_e32 v178, v166, v167
	v_add_f32_e32 v177, v177, v178
	v_add_f32_e32 v176, v176, v177
	v_add_f32_e32 v177, v160, v161
	v_add_f32_e32 v178, v162, v163
	v_add_f32_e32 v177, v177, v178
	v_add_f32_e32 v176, v176, v177
	v_add_f32_e32 v177, v172, v173
	v_add_f32_e32 v178, v174, v175
	v_add_f32_e32 v177, v177, v178
	v_add_f32_e32 v176, v176, v177
	s_mov_b32 s98, 0x800000
	v_fmamk_f32 v176, v176, 0x3a800000, v241
	v_mul_f32_e32 v177, 0x4b800000, v176
	v_cmp_gt_f32_e32 vcc, s98, v176
	s_nop 1
	v_cndmask_b32_e32 v176, v176, v177, vcc
	v_rsq_f32_e32 v176, v176
	s_nop 0
	v_mul_f32_e32 v177, 0x45800000, v176
	v_cndmask_b32_e32 v4, v176, v177, vcc
	ds_write_b32 v9, v4
	s_or_b64 exec, exec, s[8:9]
	v_lshrrev_b32_e32 v9, 1, v146
	v_and_b32_e32 v4, 15, v146
	v_and_b32_e32 v9, 24, v9
	v_lshl_or_b32 v147, s14, 6, v4
	v_lshlrev_b32_e32 v10, 1, v9
	v_lshl_or_b32 v4, v4, 6, v10
	v_lshlrev_b32_e32 v10, 2, v147
	s_lshl_b32 s8, s14, 13
	v_and_b32_e32 v11, 32, v10
	v_bitop3_b32 v11, v4, s8, v11 bitop3:0xde
	s_lshl_b32 s8, s15, 5
	s_and_b32 s10, s8, 0x60
	v_lshlrev_b32_e32 v12, 2, v146
	s_lshl_b32 s8, s10, 7
	v_and_b32_e32 v13, 32, v12
	v_bitop3_b32 v148, v4, s8, v13 bitop3:0xde
	v_lshlrev_b32_e32 v4, 14, v5
	v_and_b32_e32 v4, 0xffff8000, v4
	v_lshl_add_u32 v3, v3, 11, v4
	v_and_b32_e32 v4, 1, v5
	v_lshl_or_b32 v3, v4, 6, v3
	v_lshl_add_u32 v4, v6, 1, v3
	v_lshlrev_b32_e32 v3, 14, v2
	s_add_i32 s11, 0, 0x21040
	v_readlane_b32 s16, v253, 46
	v_and_b32_e32 v3, 0xffff8000, v3
	s_cmpk_lt_u32 s13, 0x100
	v_readlane_b32 s18, v253, 48
	v_lshl_add_u32 v3, v7, 11, v3
	v_and_b32_e32 v2, 1, v2
	s_cselect_b64 s[8:9], -1, 0
	v_or_b32_e32 v151, s10, v9
	v_readlane_b32 s19, v253, 49
	s_add_u32 s10, s18, 0x5040080
	v_lshl_or_b32 v2, v2, 6, v3
	v_add_u32_e32 v149, s11, v12
	v_add_u32_e32 v150, s11, v10
	s_addc_u32 s11, s19, 0
	v_mov_b32_e32 v5, v1
	v_lshl_add_u32 v2, v8, 1, v2
	v_mov_b32_e32 v3, v1
	v_lshl_add_u64 v[132:133], s[10:11], 0, v[4:5]
	v_lshl_add_u64 v[134:135], s[10:11], 0, v[2:3]
	v_readlane_b32 s10, v253, 52
	s_add_u32 s10, s12, s10
	v_readlane_b32 s11, v253, 54
	s_addc_u32 s11, 0, s11
	s_add_u32 s10, s18, s10
	s_addc_u32 s11, s19, s11
	s_add_u32 s30, s10, 0x100
	v_readlane_b32 s37, v253, 3
	v_readlane_b32 s38, v253, 4
	v_readlane_b32 s18, v253, 5
	v_readlane_b32 s20, v253, 16
	s_addc_u32 s31, s11, 0
	s_mov_b32 s33, 0
	v_add_u32_e32 v152, 0, v11
	v_readlane_b32 s19, v253, 6
	v_readlane_b32 s21, v253, 17
	v_readlane_b32 s34, v251, 0
	s_mov_b32 s36, s37
	s_mov_b32 s35, s38
	v_readlane_b32 s17, v253, 47
	v_readlane_b32 s99, v253, 41
	v_mov_b32_e32 v227, 0x3e8
	v_mov_b32_e32 v226, 0
	v_mov_b32_e32 v237, 0
	s_cmp_eq_u32 s99, 1
	s_cbranch_scc1 .Lbgc_k
	s_cmp_eq_u32 s99, 9
	s_cbranch_scc1 .Lbgc_v
	s_branch .Lbgc_done
.Lbgc_k:
	v_readlane_b32 s100, v253, 42
	v_readlane_b32 s101, v253, 43
	s_nop 0
	s_load_dwordx2 s[100:101], s[100:101], 0x18
	v_mov_b32_e32 v238, 0x912e000
	s_branch .Lbgc_common
.Lbgc_v:
	v_readlane_b32 s100, v253, 42
	v_readlane_b32 s101, v253, 43
	s_nop 0
	s_load_dwordx2 s[100:101], s[100:101], 0x20
	v_mov_b32_e32 v238, 0x1212e000
.Lbgc_common:
	s_lshl_b32 s99, s34, 9
	v_add_u32_e32 v226, s99, v201
	v_lshlrev_b32_e32 v236, 4, v226
	s_waitcnt lgkmcnt(0)
	v_lshl_add_u64 v[228:229], s[100:101], 0, v[236:237]
	s_mov_b32 s100, 0xffe00000
	s_mov_b32 s101, -1
	v_lshl_add_u64 v[228:229], v[228:229], 0, s[100:101]
	v_readlane_b32 s100, v253, 42
	v_readlane_b32 s101, v253, 43
	s_nop 0
	s_load_dwordx2 s[100:101], s[100:101], 0xd8
	v_add_u32_e32 v236, v238, v236
	s_waitcnt lgkmcnt(0)
	v_lshl_add_u64 v[230:231], s[100:101], 0, v[236:237]
	s_mov_b32 s100, 0xffdffc00
	s_mov_b32 s101, -1
	v_lshl_add_u64 v[230:231], v[230:231], 0, s[100:101]
	v_subrev_u32_e32 v226, 64, v226
	v_mov_b32_e32 v227, -1
	s_mov_b32 s99, 1
	s_branch .Lbgc_done2
.Lbgc_done:
	s_mov_b32 s99, 0
.Lbgc_done2:
	s_mov_b64 s[100:101], 0
	s_branch .LBB0_685
	s_nop 0
	s_nop 0
	s_nop 0
	s_nop 0
	s_nop 0
	s_nop 0
	s_nop 0

.LBB0_688:
	s_cmp_eq_u32 s99, 0
	s_cbranch_scc1 .Lbgc_it_skip
	s_mov_b64 exec, s[100:101]
	s_nop 0
	global_store_dwordx4 v[230:231], v[232:235], off nt
	s_mov_b64 exec, -1
	v_add_u32_e32 v226, 64, v226
	v_add_u32_e32 v227, 1, v227
	v_cmp_le_i32_e32 vcc, 0x1ffc0, v226
	v_subrev_u32_e32 v236, 0x1ffc0, v226
	s_nop 0
	v_cndmask_b32_e32 v226, v226, v236, vcc
	v_cndmask_b32_e64 v238, 0, 1, vcc
	v_add_u32_e32 v227, v227, v238
	v_mov_b32_e32 v236, 0x200400
	v_mov_b32_e32 v238, 0x200800
	v_cndmask_b32_e32 v236, v236, v238, vcc
	v_lshl_add_u64 v[228:229], v[228:229], 0, v[236:237]
	v_lshl_add_u64 v[230:231], v[230:231], 0, v[236:237]
	v_cmp_gt_i32_e32 vcc, 64, v227
	s_nop 1
	s_mov_b64 s[100:101], vcc
	s_mov_b64 exec, vcc
	s_nop 0
	global_load_dwordx4 v[232:235], v[228:229], off nt
	s_mov_b64 exec, -1
	s_cmp_lg_u64 s[100:101], 0
	s_cselect_b32 s99, 1, 0

.LBB0_698:
	s_cmp_eq_u32 s99, 0
	s_cbranch_scc1 .Lbgc_fl_done
	s_waitcnt vmcnt(0)
.Lbgc_fl:
	s_mov_b64 exec, s[100:101]
	s_nop 0
	global_store_dwordx4 v[230:231], v[232:235], off nt
	s_mov_b64 exec, -1
	v_add_u32_e32 v226, 64, v226
	v_add_u32_e32 v227, 1, v227
	v_cmp_le_i32_e32 vcc, 0x1ffc0, v226
	v_subrev_u32_e32 v236, 0x1ffc0, v226
	s_nop 0
	v_cndmask_b32_e32 v226, v226, v236, vcc
	v_cndmask_b32_e64 v238, 0, 1, vcc
	v_add_u32_e32 v227, v227, v238
	v_mov_b32_e32 v236, 0x200400
	v_mov_b32_e32 v238, 0x200800
	v_cndmask_b32_e32 v236, v236, v238, vcc
	v_lshl_add_u64 v[228:229], v[228:229], 0, v[236:237]
	v_lshl_add_u64 v[230:231], v[230:231], 0, v[236:237]
	v_cmp_gt_i32_e32 vcc, 64, v227
	s_nop 1
	s_mov_b64 s[100:101], vcc
	s_cmp_eq_u64 s[100:101], 0
	s_cbranch_scc1 .Lbgc_fl_done
	s_mov_b64 exec, vcc
	s_nop 0
	global_load_dwordx4 v[232:235], v[228:229], off nt
	s_mov_b64 exec, -1
	s_waitcnt vmcnt(0)
	s_branch .Lbgc_fl

.LBB0_710:
	s_or_b64 exec, exec, s[8:9]
	v_lshlrev_b32_e32 v10, 16, v6
	v_and_b32_e32 v6, 0xffff0000, v6
	v_mul_f32_e32 v6, v6, v6
	v_fmac_f32_e32 v6, v10, v10
	v_lshlrev_b32_e32 v10, 16, v7
	v_fmac_f32_e32 v6, v10, v10
	v_and_b32_e32 v7, 0xffff0000, v7
	v_fmac_f32_e32 v6, v7, v7
	v_lshlrev_b32_e32 v7, 16, v8
	v_fmac_f32_e32 v6, v7, v7
	v_and_b32_e32 v7, 0xffff0000, v8
	v_fmac_f32_e32 v6, v7, v7
	v_lshlrev_b32_e32 v7, 16, v9
	v_fmac_f32_e32 v6, v7, v7
	v_and_b32_e32 v7, 0xffff0000, v9
	v_fmac_f32_e32 v6, v7, v7
	v_lshlrev_b32_e32 v7, 16, v2
	v_and_b32_e32 v2, 0xffff0000, v2
	v_mul_f32_e32 v2, v2, v2
	v_fmac_f32_e32 v2, v7, v7
	v_lshlrev_b32_e32 v7, 16, v3
	v_fmac_f32_e32 v2, v7, v7
	v_and_b32_e32 v3, 0xffff0000, v3
	v_fmac_f32_e32 v2, v3, v3
	v_lshlrev_b32_e32 v3, 16, v4
	v_fmac_f32_e32 v2, v3, v3
	v_and_b32_e32 v3, 0xffff0000, v4
	v_fmac_f32_e32 v2, v3, v3
	v_lshlrev_b32_e32 v3, 16, v5
	v_fmac_f32_e32 v2, v3, v3
	v_and_b32_e32 v3, 0xffff0000, v5
	v_fmac_f32_e32 v2, v3, v3
	v_add_f32_e32 v2, v6, v2
	ds_bpermute_b32 v0, v0, v2
	s_waitcnt lgkmcnt(0)
	v_add_f32_e32 v0, v2, v0
	ds_bpermute_b32 v2, v42, v0
	s_waitcnt lgkmcnt(0)
	v_add_f32_e32 v0, v0, v2
	ds_bpermute_b32 v2, v43, v0
	s_waitcnt lgkmcnt(0)
	v_add_f32_e32 v0, v0, v2
	ds_bpermute_b32 v2, v44, v0
	s_waitcnt lgkmcnt(0)
	v_add_f32_e32 v0, v0, v2
	ds_bpermute_b32 v2, v45, v0
	s_waitcnt lgkmcnt(0)
	v_add_f32_e32 v0, v0, v2
	ds_bpermute_b32 v2, v46, v0
	s_and_saveexec_b64 s[4:5], vcc
	s_cbranch_execz .LBB0_703
	s_waitcnt lgkmcnt(0)
	v_add_f32_e32 v0, v0, v2
	v_fmamk_f32 v0, v0, 0x3a800000, v241
	s_mov_b32 s8, 0x800000
	v_mul_f32_e32 v2, 0x4b800000, v0
	v_cmp_gt_f32_e32 vcc, s8, v0
	s_nop 1
	v_cndmask_b32_e32 v0, v0, v2, vcc
	v_rsq_f32_e32 v0, v0
	s_nop 0
	v_mul_f32_e32 v2, 0x45800000, v0
	v_cndmask_b32_e32 v0, v0, v2, vcc
	ds_write_b32 v47, v0 offset:32780
	s_branch .LBB0_703
	s_nop 0
	s_nop 0
	s_nop 0
	s_nop 0
	s_nop 0
	s_nop 0

.LBB0_761:
	s_or_b64 exec, exec, s[4:5]
	v_mov_b32_e32 v0, v201
	v_readlane_b32 s2, v252, 25
	s_barrier
	s_nop 0
	v_add_u32_e32 v2, s2, v0
	s_mov_b32 s2, 0xffe000
	s_mov_b64 vcc, 0
	s_and_saveexec_b64 s[8:9], vcc
	v_readlane_b32 s16, v251, 1
	v_readlane_b32 s17, v251, 2
	v_readlane_b32 s24, v253, 46
	v_readlane_b32 s17, v252, 26
	v_readlane_b32 s18, v253, 12
	v_readlane_b32 s19, v253, 13
	s_mov_b32 s20, 0x7ff000
	s_mov_b32 s21, 0x1002005
	v_readlane_b32 s25, v253, 47
	v_readlane_b32 s26, v253, 48
	v_readlane_b32 s27, v253, 49
	s_cbranch_execz .LBB0_764
	v_readlane_b32 s10, v253, 42
	v_readlane_b32 s11, v253, 43
	s_load_dwordx4 s[4:7], s[10:11], 0x18
	s_mov_b64 s[10:11], 0
